# deferral raised to 10240 conversion items (all of w_up[3], w_down[3] and half of w_down[2]) in the QKV-l2 idle window
# baseline (speedup 1.0000x reference)
.Lcvb_loop:
	s_cmp_ge_u32 s15, 0x2800
	s_cbranch_scc1 .Lcvb_exit
	s_add_i32 s2, s15, 0x3000
	s_cmp_lt_u32 s15, 0x1000
	s_cbranch_scc1 .Lcvb_go
	s_add_i32 s2, s15, 0x5800

.Lcva_loop:
	s_cmp_ge_u32 s15, 0x9300
	s_cbranch_scc1 .Lcva_exit
	s_cmp_lt_u32 s15, 0x3000
	s_cbranch_scc1 .Lcva_go
	s_cmp_lt_u32 s15, 0x4000
	s_cbranch_scc1 .Lcva_next
	s_cmp_lt_u32 s15, 0x6800
	s_cbranch_scc1 .Lcva_go
	s_cmp_lt_u32 s15, 0x8000
	s_cbranch_scc1 .Lcva_next
